# flat barrier: two staggered polls in flight per workgroup
# baseline (speedup 1.0000x reference)
.Lbarf_poll0:
	s_mov_b32 s0, 0
	global_load_dword v6, v7, s[4:5] sc1
	s_sleep 20
.Lbarf_spin0:
	global_load_dword v8, v7, s[4:5] sc1
	s_waitcnt vmcnt(1)
	v_cmp_ge_u32_e32 vcc, v6, v5
	s_cbranch_vccnz .Lbarf_done0
	global_load_dword v6, v7, s[4:5] sc1
	s_waitcnt vmcnt(1)
	v_cmp_ge_u32_e32 vcc, v8, v5
	s_cbranch_vccnz .Lbarf_done0
	s_add_u32 s0, s0, 1
	s_cmp_lt_u32 s0, 0x20000
	s_cbranch_scc1 .Lbarf_spin0
	v_readlane_b32 s6, v254, 5
	v_readlane_b32 s7, v254, 6
	v_mov_b32_e32 v4, 1
	s_nop 3
	global_atomic_add v7, v4, s[6:7]
.Lbarf_done0:
	buffer_inv sc1
	s_waitcnt vmcnt(0)

.Lbarf_done7:
	buffer_inv sc1
	s_waitcnt vmcnt(0)
	s_getpc_b64 s[98:99]
